# P4 v^T epilogue fully hand-written: row scales once, scale+pack per accumulator quad, tile staged in LDS and copied out as whole rows (the compiled one spent ~1000 instructions per wave on per-store a
# baseline (speedup 1.0000x reference)
.LBB0_627:
	s_lshl_b32 s8, s15, 8
	s_lshl_b32 s9, s14, 8
	s_cmp_lt_u32 s8, 0x4000
	s_cbranch_scc0 .Lvte_sample
	s_lshr_b32 s10, s8, 13
	s_lshl_b32 s10, s10, 9
	s_add_i32 s10, s10, s9
	s_lshl_b32 s10, s10, 13
	s_and_b32 s11, s8, 0x1fff
	s_or_b32 s101, s10, s11
	s_mov_b32 s98, 13
	s_branch .Lvte_go
.Lvte_sample:
	s_sub_u32 s11, s8, 0x4000
	s_lshr_b32 s10, s11, 12
	s_lshl_b32 s10, s10, 9
	s_add_i32 s10, s10, s9
	s_lshl_b32 s10, s10, 12
	s_and_b32 s11, s11, 0xfff
	s_or_b32 s10, s10, s11
	s_add_u32 s101, s10, 0x800000
	s_mov_b32 s98, 12
.Lvte_go:
	v_and_b32_e32 v146, 15, v0
	v_bfe_u32 v147, v0, 4, 2
	v_bfe_u32 v148, v0, 6, 2
	v_bfe_u32 v149, v0, 8, 1
	v_lshl_add_u32 v150, v148, 3, v147
	v_lshl_add_u32 v151, v149, 6, v146
	v_lshlrev_b32_e32 v152, 4, v150
	s_lshl_b32 s10, s8, 2
	v_add_u32_e32 v152, s10, v152
	global_load_dwordx4 v[130:133], v152, s[40:41]
	global_load_dwordx4 v[134:137], v152, s[40:41] offset:64
	global_load_dwordx4 v[138:141], v152, s[40:41] offset:512
	global_load_dwordx4 v[142:145], v152, s[40:41] offset:576
	v_mul_u32_u24_e32 v153, 0x210, v151
	v_lshl_add_u32 v153, v150, 3, v153
	v_add_u32_e32 v154, 0x10800, v153
	v_mov_b32_e32 v155, s64
	s_waitcnt vmcnt(0)
	s_barrier
	v_fma_f32 v130, v130, s62, v155
	v_fma_f32 v131, v131, s62, v155
	v_fma_f32 v132, v132, s62, v155
	v_fma_f32 v133, v133, s62, v155
	v_fma_f32 v134, v134, s62, v155
	v_fma_f32 v135, v135, s62, v155
	v_fma_f32 v136, v136, s62, v155
	v_fma_f32 v137, v137, s62, v155
	v_fma_f32 v138, v138, s62, v155
	v_fma_f32 v139, v139, s62, v155
	v_fma_f32 v140, v140, s62, v155
	v_fma_f32 v141, v141, s62, v155
	v_fma_f32 v142, v142, s62, v155
	v_fma_f32 v143, v143, s62, v155
	v_fma_f32 v144, v144, s62, v155
	v_fma_f32 v145, v145, s62, v155
	v_rsq_f32_e32 v130, v130
	v_rsq_f32_e32 v131, v131
	v_rsq_f32_e32 v132, v132
	v_rsq_f32_e32 v133, v133
	v_rsq_f32_e32 v134, v134
	v_rsq_f32_e32 v135, v135
	v_rsq_f32_e32 v136, v136
	v_rsq_f32_e32 v137, v137
	v_rsq_f32_e32 v138, v138
	v_rsq_f32_e32 v139, v139
	v_rsq_f32_e32 v140, v140
	v_rsq_f32_e32 v141, v141
	v_rsq_f32_e32 v142, v142
	v_rsq_f32_e32 v143, v143
	v_rsq_f32_e32 v144, v144
	v_rsq_f32_e32 v145, v145
	s_nop 0
	v_pk_mul_f32 v[126:127], v[126:127], v[130:131]
	v_pk_mul_f32 v[128:129], v[128:129], v[132:133]
	v_cvt_pk_bf16_f32 v126, v126, v127
	v_cvt_pk_bf16_f32 v127, v128, v129
	ds_write_b64 v153, v[126:127]
	v_pk_mul_f32 v[122:123], v[122:123], v[130:131]
	v_pk_mul_f32 v[124:125], v[124:125], v[132:133]
	v_cvt_pk_bf16_f32 v122, v122, v123
	v_cvt_pk_bf16_f32 v123, v124, v125
	ds_write_b64 v153, v[122:123] offset:8448
	v_pk_mul_f32 v[118:119], v[118:119], v[130:131]
	v_pk_mul_f32 v[120:121], v[120:121], v[132:133]
	v_cvt_pk_bf16_f32 v118, v118, v119
	v_cvt_pk_bf16_f32 v119, v120, v121
	ds_write_b64 v153, v[118:119] offset:16896
	v_pk_mul_f32 v[110:111], v[110:111], v[130:131]
	v_pk_mul_f32 v[112:113], v[112:113], v[132:133]
	v_cvt_pk_bf16_f32 v110, v110, v111
	v_cvt_pk_bf16_f32 v111, v112, v113
	ds_write_b64 v153, v[110:111] offset:25344
	v_pk_mul_f32 v[114:115], v[114:115], v[130:131]
	v_pk_mul_f32 v[116:117], v[116:117], v[132:133]
	v_cvt_pk_bf16_f32 v114, v114, v115
	v_cvt_pk_bf16_f32 v115, v116, v117
	ds_write_b64 v154, v[114:115]
	v_pk_mul_f32 v[106:107], v[106:107], v[130:131]
	v_pk_mul_f32 v[108:109], v[108:109], v[132:133]
	v_cvt_pk_bf16_f32 v106, v106, v107
	v_cvt_pk_bf16_f32 v107, v108, v109
	ds_write_b64 v154, v[106:107] offset:8448
	v_pk_mul_f32 v[102:103], v[102:103], v[130:131]
	v_pk_mul_f32 v[104:105], v[104:105], v[132:133]
	v_cvt_pk_bf16_f32 v102, v102, v103
	v_cvt_pk_bf16_f32 v103, v104, v105
	ds_write_b64 v154, v[102:103] offset:16896
	v_pk_mul_f32 v[98:99], v[98:99], v[130:131]
	v_pk_mul_f32 v[100:101], v[100:101], v[132:133]
	v_cvt_pk_bf16_f32 v98, v98, v99
	v_cvt_pk_bf16_f32 v99, v100, v101
	ds_write_b64 v154, v[98:99] offset:25344
	v_pk_mul_f32 v[94:95], v[94:95], v[134:135]
	v_pk_mul_f32 v[96:97], v[96:97], v[136:137]
	v_cvt_pk_bf16_f32 v94, v94, v95
	v_cvt_pk_bf16_f32 v95, v96, v97
	ds_write_b64 v153, v[94:95] offset:32
	v_pk_mul_f32 v[90:91], v[90:91], v[134:135]
	v_pk_mul_f32 v[92:93], v[92:93], v[136:137]
	v_cvt_pk_bf16_f32 v90, v90, v91
	v_cvt_pk_bf16_f32 v91, v92, v93
	ds_write_b64 v153, v[90:91] offset:8480
	v_pk_mul_f32 v[86:87], v[86:87], v[134:135]
	v_pk_mul_f32 v[88:89], v[88:89], v[136:137]
	v_cvt_pk_bf16_f32 v86, v86, v87
	v_cvt_pk_bf16_f32 v87, v88, v89
	ds_write_b64 v153, v[86:87] offset:16928
	v_pk_mul_f32 v[78:79], v[78:79], v[134:135]
	v_pk_mul_f32 v[80:81], v[80:81], v[136:137]
	v_cvt_pk_bf16_f32 v78, v78, v79
	v_cvt_pk_bf16_f32 v79, v80, v81
	ds_write_b64 v153, v[78:79] offset:25376
	v_pk_mul_f32 v[82:83], v[82:83], v[134:135]
	v_pk_mul_f32 v[84:85], v[84:85], v[136:137]
	v_cvt_pk_bf16_f32 v82, v82, v83
	v_cvt_pk_bf16_f32 v83, v84, v85
	ds_write_b64 v154, v[82:83] offset:32
	v_pk_mul_f32 v[74:75], v[74:75], v[134:135]
	v_pk_mul_f32 v[76:77], v[76:77], v[136:137]
	v_cvt_pk_bf16_f32 v74, v74, v75
	v_cvt_pk_bf16_f32 v75, v76, v77
	ds_write_b64 v154, v[74:75] offset:8480
	v_pk_mul_f32 v[70:71], v[70:71], v[134:135]
	v_pk_mul_f32 v[72:73], v[72:73], v[136:137]
	v_cvt_pk_bf16_f32 v70, v70, v71
	v_cvt_pk_bf16_f32 v71, v72, v73
	ds_write_b64 v154, v[70:71] offset:16928
	v_pk_mul_f32 v[66:67], v[66:67], v[134:135]
	v_pk_mul_f32 v[68:69], v[68:69], v[136:137]
	v_cvt_pk_bf16_f32 v66, v66, v67
	v_cvt_pk_bf16_f32 v67, v68, v69
	ds_write_b64 v154, v[66:67] offset:25376
	v_pk_mul_f32 v[62:63], v[62:63], v[138:139]
	v_pk_mul_f32 v[64:65], v[64:65], v[140:141]
	v_cvt_pk_bf16_f32 v62, v62, v63
	v_cvt_pk_bf16_f32 v63, v64, v65
	ds_write_b64 v153, v[62:63] offset:256
	v_pk_mul_f32 v[58:59], v[58:59], v[138:139]
	v_pk_mul_f32 v[60:61], v[60:61], v[140:141]
	v_cvt_pk_bf16_f32 v58, v58, v59
	v_cvt_pk_bf16_f32 v59, v60, v61
	ds_write_b64 v153, v[58:59] offset:8704
	v_pk_mul_f32 v[54:55], v[54:55], v[138:139]
	v_pk_mul_f32 v[56:57], v[56:57], v[140:141]
	v_cvt_pk_bf16_f32 v54, v54, v55
	v_cvt_pk_bf16_f32 v55, v56, v57
	ds_write_b64 v153, v[54:55] offset:17152
	v_pk_mul_f32 v[46:47], v[46:47], v[138:139]
	v_pk_mul_f32 v[48:49], v[48:49], v[140:141]
	v_cvt_pk_bf16_f32 v46, v46, v47
	v_cvt_pk_bf16_f32 v47, v48, v49
	ds_write_b64 v153, v[46:47] offset:25600
	v_pk_mul_f32 v[50:51], v[50:51], v[138:139]
	v_pk_mul_f32 v[52:53], v[52:53], v[140:141]
	v_cvt_pk_bf16_f32 v50, v50, v51
	v_cvt_pk_bf16_f32 v51, v52, v53
	ds_write_b64 v154, v[50:51] offset:256
	v_pk_mul_f32 v[42:43], v[42:43], v[138:139]
	v_pk_mul_f32 v[44:45], v[44:45], v[140:141]
	v_cvt_pk_bf16_f32 v42, v42, v43
	v_cvt_pk_bf16_f32 v43, v44, v45
	ds_write_b64 v154, v[42:43] offset:8704
	v_pk_mul_f32 v[38:39], v[38:39], v[138:139]
	v_pk_mul_f32 v[40:41], v[40:41], v[140:141]
	v_cvt_pk_bf16_f32 v38, v38, v39
	v_cvt_pk_bf16_f32 v39, v40, v41
	ds_write_b64 v154, v[38:39] offset:17152
	v_pk_mul_f32 v[34:35], v[34:35], v[138:139]
	v_pk_mul_f32 v[36:37], v[36:37], v[140:141]
	v_cvt_pk_bf16_f32 v34, v34, v35
	v_cvt_pk_bf16_f32 v35, v36, v37
	ds_write_b64 v154, v[34:35] offset:25600
	v_pk_mul_f32 v[30:31], v[30:31], v[142:143]
	v_pk_mul_f32 v[32:33], v[32:33], v[144:145]
	v_cvt_pk_bf16_f32 v30, v30, v31
	v_cvt_pk_bf16_f32 v31, v32, v33
	ds_write_b64 v153, v[30:31] offset:288
	v_pk_mul_f32 v[26:27], v[26:27], v[142:143]
	v_pk_mul_f32 v[28:29], v[28:29], v[144:145]
	v_cvt_pk_bf16_f32 v26, v26, v27
	v_cvt_pk_bf16_f32 v27, v28, v29
	ds_write_b64 v153, v[26:27] offset:8736
	v_pk_mul_f32 v[22:23], v[22:23], v[142:143]
	v_pk_mul_f32 v[24:25], v[24:25], v[144:145]
	v_cvt_pk_bf16_f32 v22, v22, v23
	v_cvt_pk_bf16_f32 v23, v24, v25
	ds_write_b64 v153, v[22:23] offset:17184
	v_pk_mul_f32 v[14:15], v[14:15], v[142:143]
	v_pk_mul_f32 v[16:17], v[16:17], v[144:145]
	v_cvt_pk_bf16_f32 v14, v14, v15
	v_cvt_pk_bf16_f32 v15, v16, v17
	ds_write_b64 v153, v[14:15] offset:25632
	v_pk_mul_f32 v[18:19], v[18:19], v[142:143]
	v_pk_mul_f32 v[20:21], v[20:21], v[144:145]
	v_cvt_pk_bf16_f32 v18, v18, v19
	v_cvt_pk_bf16_f32 v19, v20, v21
	ds_write_b64 v154, v[18:19] offset:288
	v_pk_mul_f32 v[10:11], v[10:11], v[142:143]
	v_pk_mul_f32 v[12:13], v[12:13], v[144:145]
	v_cvt_pk_bf16_f32 v10, v10, v11
	v_cvt_pk_bf16_f32 v11, v12, v13
	ds_write_b64 v154, v[10:11] offset:8736
	v_pk_mul_f32 v[6:7], v[6:7], v[142:143]
	v_pk_mul_f32 v[8:9], v[8:9], v[144:145]
	v_cvt_pk_bf16_f32 v6, v6, v7
	v_cvt_pk_bf16_f32 v7, v8, v9
	ds_write_b64 v154, v[6:7] offset:17184
	v_pk_mul_f32 v[2:3], v[2:3], v[142:143]
	v_pk_mul_f32 v[4:5], v[4:5], v[144:145]
	v_cvt_pk_bf16_f32 v2, v2, v3
	v_cvt_pk_bf16_f32 v3, v4, v5
	ds_write_b64 v154, v[2:3] offset:25632
	s_waitcnt lgkmcnt(0)
	s_barrier
	v_lshrrev_b32_e32 v2, 5, v0
	v_and_b32_e32 v3, 31, v0
	v_mul_u32_u24_e32 v4, 0x210, v2
	v_lshl_add_u32 v4, v3, 4, v4
	v_add_u32_e32 v5, 0x10800, v4
	s_add_i32 s99, s98, 1
	v_lshlrev_b32_e32 v6, s99, v2
	v_lshl_add_u32 v6, v3, 4, v6
	s_lshl_b32 s100, s101, 1
	v_add_u32_e32 v6, s100, v6
	v_mov_b32_e32 v7, 0
	v_lshl_add_u64 v[6:7], v[6:7], 0, s[46:47]
	s_add_i32 s99, s98, 5
	s_lshl_b32 s100, 1, s99
	s_mov_b32 s101, 0
	ds_read_b128 v[8:11], v4
	ds_read_b128 v[12:15], v4 offset:8448
	ds_read_b128 v[16:19], v4 offset:16896
	ds_read_b128 v[20:23], v4 offset:25344
	ds_read_b128 v[24:27], v4 offset:33792
	ds_read_b128 v[28:31], v4 offset:42240
	ds_read_b128 v[32:35], v4 offset:50688
	ds_read_b128 v[36:39], v4 offset:59136
	ds_read_b128 v[40:43], v5
	ds_read_b128 v[44:47], v5 offset:8448
	ds_read_b128 v[48:51], v5 offset:16896
	ds_read_b128 v[52:55], v5 offset:25344
	ds_read_b128 v[56:59], v5 offset:33792
	ds_read_b128 v[60:63], v5 offset:42240
	ds_read_b128 v[64:67], v5 offset:50688
	ds_read_b128 v[68:71], v5 offset:59136
	s_waitcnt lgkmcnt(15)
	global_store_dwordx4 v[6:7], v[8:11], off
	v_lshl_add_u64 v[6:7], v[6:7], 0, s[100:101]
	s_waitcnt lgkmcnt(14)
	global_store_dwordx4 v[6:7], v[12:15], off
	v_lshl_add_u64 v[6:7], v[6:7], 0, s[100:101]
	s_waitcnt lgkmcnt(13)
	global_store_dwordx4 v[6:7], v[16:19], off
	v_lshl_add_u64 v[6:7], v[6:7], 0, s[100:101]
	s_waitcnt lgkmcnt(12)
	global_store_dwordx4 v[6:7], v[20:23], off
	v_lshl_add_u64 v[6:7], v[6:7], 0, s[100:101]
	s_waitcnt lgkmcnt(11)
	global_store_dwordx4 v[6:7], v[24:27], off
	v_lshl_add_u64 v[6:7], v[6:7], 0, s[100:101]
	s_waitcnt lgkmcnt(10)
	global_store_dwordx4 v[6:7], v[28:31], off
	v_lshl_add_u64 v[6:7], v[6:7], 0, s[100:101]
	s_waitcnt lgkmcnt(9)
	global_store_dwordx4 v[6:7], v[32:35], off
	v_lshl_add_u64 v[6:7], v[6:7], 0, s[100:101]
	s_waitcnt lgkmcnt(8)
	global_store_dwordx4 v[6:7], v[36:39], off
	v_lshl_add_u64 v[6:7], v[6:7], 0, s[100:101]
	s_waitcnt lgkmcnt(7)
	global_store_dwordx4 v[6:7], v[40:43], off
	v_lshl_add_u64 v[6:7], v[6:7], 0, s[100:101]
	s_waitcnt lgkmcnt(6)
	global_store_dwordx4 v[6:7], v[44:47], off
	v_lshl_add_u64 v[6:7], v[6:7], 0, s[100:101]
	s_waitcnt lgkmcnt(5)
	global_store_dwordx4 v[6:7], v[48:51], off
	v_lshl_add_u64 v[6:7], v[6:7], 0, s[100:101]
	s_waitcnt lgkmcnt(4)
	global_store_dwordx4 v[6:7], v[52:55], off
	v_lshl_add_u64 v[6:7], v[6:7], 0, s[100:101]
	s_waitcnt lgkmcnt(3)
	global_store_dwordx4 v[6:7], v[56:59], off
	v_lshl_add_u64 v[6:7], v[6:7], 0, s[100:101]
	s_waitcnt lgkmcnt(2)
	global_store_dwordx4 v[6:7], v[60:63], off
	v_lshl_add_u64 v[6:7], v[6:7], 0, s[100:101]
	s_waitcnt lgkmcnt(1)
	global_store_dwordx4 v[6:7], v[64:67], off
	v_lshl_add_u64 v[6:7], v[6:7], 0, s[100:101]
	s_waitcnt lgkmcnt(0)
	global_store_dwordx4 v[6:7], v[68:71], off
	v_lshl_add_u64 v[6:7], v[6:7], 0, s[100:101]
	s_and_b64 vcc, exec, s[6:7]
	s_mov_b64 s[0:1], -1
	s_cbranch_vccnz .LBB0_614
	s_andn2_b64 vcc, exec, s[50:51]
	s_cbranch_vccnz .LBB0_613
	s_barrier
	s_branch .LBB0_613
